# MLA tile loop: 32 per-score subtractions replaced by 16 packed subtractions (instruction selection), on top of the stacked version
# baseline (speedup 1.0000x reference)
; #define LAS __attribute__((address_space(3)))
; DI float ex2(float x) { return __builtin_amdgcn_exp2f(x); }
; DI float shx(float v, int lane, int m) { return __builtin_bit_cast(float, __builtin_amdgcn_ds_bpermute((lane ^ m) << 2, __builtin_bit_cast(int, v))); }
; #define MFMA32(a, b, c) __builtin_amdgcn_mfma_f32_32x32x16_bf16((a), (b), (c), 0, 0, 0)
; DI bf16x8 tr_frag(LAS const unsigned char* p, int hi_off) { s16x4 lo = trr(p), hi = trr(p + hi_off); return __builtin_shufflevector(lo, hi, 0, 1, 2, 3, 4, 5, 6, 7); }
; DI void mla_item(int g_wave, LAS unsigned char* lds, const bf16_t* QN, const bf16_t* QR, const bf16_t* KN, const bf16_t* KRb, const bf16_t* VM, bf16_t* MIX,
;                  int kvbase, int qrow0, int nq, int head, int ntiles, int wt) {
;     ...
;             for (int s = 0; s < 6; ++s) {
;                 const bf16x8 a0 = *(LAS const bf16x8*)(base + r * KST + (16 * s + 8 * h) * 2);
;                 const bf16x8 a1 = *(LAS const bf16x8*)(base + (32 + r) * KST + (16 * s + 8 * h) * 2);
;                 s0 = MFMA32(a0, qf[s], s0); s1 = MFMA32(a1, qf[s], s1);
;             }
;             float mx = s0[0];
; #pragma unroll
;             for (int i = 0; i < 16; ++i) { mx = fmaxf(mx, s0[i]); mx = fmaxf(mx, s1[i]); }
;             mx = fmaxf(mx, shx(mx, lane, 32));
;             const float m_new = fmaxf(m_run, mx), alpha = ex2(m_run - m_new);
;             m_run = m_new;
;             float ls = 0.f;
; #pragma unroll
;             for (int i = 0; i < 16; ++i) { s0[i] = ex2(s0[i] - m_new); s1[i] = ex2(s1[i] - m_new); ls += s0[i] + s1[i]; }
;             l_run = l_run * alpha + ls;
; #pragma unroll
;             for (int i = 0; i < 16; ++i) { o0[i] *= alpha; o1[i] *= alpha; }
;             LAS const unsigned char* vb = base + KB;
; #pragma unroll
;             for (int kt = 0; kt < 2; ++kt)
; #pragma unroll
;                 for (int ss = 0; ss < 2; ++ss) {
;                     const bf16x8 pb = packfrag(kt == 0 ? s0 : s1, ss);
;                     LAS const unsigned char* vp = vb + (32 * kt + 16 * ss + 4 * h + tq) * VST + (16 * blk + 4 * tp) * 2;
;                     const bf16x8 a0 = tr_frag(vp, 8 * VST), a1 = tr_frag(vp + 64, 8 * VST);
;                     o0 = MFMA32(a0, pb, o0); o1 = MFMA32(a1, pb, o1);
.LBB0_1012:
	s_or_b64 exec, exec, s[4:5]
	v_cmp_lt_i32_e32 vcc, s7, v118
	s_and_saveexec_b64 s[4:5], vcc
	s_cbranch_execz .LBB0_1014
	s_bitcmp1_b32 s7, 0
	s_cselect_b32 s8, 0x5800, 0
	s_add_i32 s8, s8, 0
	v_add3_u32 v109, s8, v122, v100
	ds_read_b128 v[32:35], v109 offset:6656
	ds_read_b128 v[36:39], v109
	ds_read_b128 v[110:113], v109 offset:32
	ds_read_b128 v[124:127], v109 offset:6688
	s_waitcnt lgkmcnt(2)
	v_mfma_f32_32x32x16_bf16 v[48:63], v[36:39], v[84:87], 0
	v_mfma_f32_32x32x16_bf16 v[32:47], v[32:35], v[84:87], 0
	s_waitcnt lgkmcnt(1)
	v_mfma_f32_32x32x16_bf16 v[48:63], v[110:113], v[80:83], v[48:63]
	s_waitcnt lgkmcnt(0)
	v_mfma_f32_32x32x16_bf16 v[32:47], v[124:127], v[80:83], v[32:47]
	ds_read_b128 v[110:113], v109 offset:64
	ds_read_b128 v[124:127], v109 offset:6720
	s_waitcnt lgkmcnt(1)
	v_mfma_f32_32x32x16_bf16 v[48:63], v[110:113], v[76:79], v[48:63]
	s_waitcnt lgkmcnt(0)
	v_mfma_f32_32x32x16_bf16 v[32:47], v[124:127], v[76:79], v[32:47]
	ds_read_b128 v[110:113], v109 offset:96
	ds_read_b128 v[124:127], v109 offset:6752
	s_waitcnt lgkmcnt(1)
	v_mfma_f32_32x32x16_bf16 v[48:63], v[110:113], v[68:71], v[48:63]
	s_waitcnt lgkmcnt(0)
	v_mfma_f32_32x32x16_bf16 v[32:47], v[124:127], v[68:71], v[32:47]
	ds_read_b128 v[110:113], v109 offset:128
	ds_read_b128 v[124:127], v109 offset:6784
	s_waitcnt lgkmcnt(1)
	v_mfma_f32_32x32x16_bf16 v[48:63], v[110:113], v[72:75], v[48:63]
	s_waitcnt lgkmcnt(0)
	v_mfma_f32_32x32x16_bf16 v[32:47], v[124:127], v[72:75], v[32:47]
	ds_read_b128 v[110:113], v109 offset:160
	ds_read_b128 v[124:127], v109 offset:6816
	s_waitcnt lgkmcnt(1)
	v_mfma_f32_32x32x16_bf16 v[48:63], v[110:113], v[64:67], v[48:63]
	s_waitcnt lgkmcnt(0)
	v_mfma_f32_32x32x16_bf16 v[32:47], v[124:127], v[64:67], v[32:47]
	s_nop 9
	v_max_f32_e32 v110, v48, v48
	s_nop 0
	v_max_f32_e32 v109, v32, v32
	v_max_f32_e32 v109, v110, v109
	v_max3_f32 v109, v109, v49, v33
	v_max3_f32 v109, v109, v50, v34
	v_max3_f32 v109, v109, v51, v35
	v_max3_f32 v109, v109, v52, v36
	v_max3_f32 v109, v109, v53, v37
	v_max3_f32 v109, v109, v54, v38
	v_max3_f32 v109, v109, v55, v39
	v_max3_f32 v109, v109, v56, v40
	v_max3_f32 v109, v109, v57, v41
	v_max3_f32 v109, v109, v58, v42
	v_max3_f32 v109, v109, v59, v43
	v_max3_f32 v109, v109, v60, v44
	v_max3_f32 v109, v109, v61, v45
	v_max3_f32 v109, v109, v62, v46
	v_max3_f32 v109, v109, v63, v47
	v_mov_b32_e32 v110, v109
	s_nop 1
	v_permlane32_swap_b32_e32 v109, v110
	v_max3_f32 v124, v108, v109, v110
	v_pk_add_f32 v[200:201], v[48:49], v[124:125] op_sel_hi:[1,0] neg_lo:[0,1] neg_hi:[0,1]
	v_pk_add_f32 v[202:203], v[50:51], v[124:125] op_sel_hi:[1,0] neg_lo:[0,1] neg_hi:[0,1]
	v_pk_add_f32 v[204:205], v[52:53], v[124:125] op_sel_hi:[1,0] neg_lo:[0,1] neg_hi:[0,1]
	v_pk_add_f32 v[206:207], v[54:55], v[124:125] op_sel_hi:[1,0] neg_lo:[0,1] neg_hi:[0,1]
	v_pk_add_f32 v[208:209], v[56:57], v[124:125] op_sel_hi:[1,0] neg_lo:[0,1] neg_hi:[0,1]
	v_pk_add_f32 v[210:211], v[58:59], v[124:125] op_sel_hi:[1,0] neg_lo:[0,1] neg_hi:[0,1]
	v_pk_add_f32 v[212:213], v[60:61], v[124:125] op_sel_hi:[1,0] neg_lo:[0,1] neg_hi:[0,1]
	v_pk_add_f32 v[214:215], v[62:63], v[124:125] op_sel_hi:[1,0] neg_lo:[0,1] neg_hi:[0,1]
	v_pk_add_f32 v[228:229], v[32:33], v[124:125] op_sel_hi:[1,0] neg_lo:[0,1] neg_hi:[0,1]
	v_pk_add_f32 v[230:231], v[34:35], v[124:125] op_sel_hi:[1,0] neg_lo:[0,1] neg_hi:[0,1]
	v_pk_add_f32 v[232:233], v[36:37], v[124:125] op_sel_hi:[1,0] neg_lo:[0,1] neg_hi:[0,1]
	v_pk_add_f32 v[234:235], v[38:39], v[124:125] op_sel_hi:[1,0] neg_lo:[0,1] neg_hi:[0,1]
	v_pk_add_f32 v[236:237], v[40:41], v[124:125] op_sel_hi:[1,0] neg_lo:[0,1] neg_hi:[0,1]
	v_pk_add_f32 v[238:239], v[42:43], v[124:125] op_sel_hi:[1,0] neg_lo:[0,1] neg_hi:[0,1]
	v_pk_add_f32 v[240:241], v[44:45], v[124:125] op_sel_hi:[1,0] neg_lo:[0,1] neg_hi:[0,1]
	v_pk_add_f32 v[242:243], v[46:47], v[124:125] op_sel_hi:[1,0] neg_lo:[0,1] neg_hi:[0,1]
	v_exp_f32_e32 v125, v228
	v_sub_f32_e32 v132, v108, v124
	v_exp_f32_e32 v108, v201
	v_exp_f32_e32 v134, v202
	v_exp_f32_e32 v126, v230
	v_exp_f32_e32 v110, v203
	v_exp_f32_e32 v133, v200
	v_exp_f32_e32 v48, v231
	v_exp_f32_e32 v135, v204
	v_exp_f32_e32 v127, v232
	v_exp_f32_e32 v112, v205
	v_exp_f32_e32 v50, v233
	v_exp_f32_e32 v136, v206
	v_exp_f32_e32 v129, v234
	v_exp_f32_e32 v130, v207
	v_exp_f32_e32 v52, v235
	v_exp_f32_e32 v138, v208
	v_exp_f32_e32 v35, v236
	v_exp_f32_e32 v54, v209
	v_exp_f32_e32 v36, v237
	v_exp_f32_e32 v139, v210
	v_exp_f32_e32 v128, v238
	v_exp_f32_e32 v56, v211
	v_exp_f32_e32 v38, v239
	v_exp_f32_e32 v140, v212
	v_exp_f32_e32 v60, v240
	v_exp_f32_e32 v58, v213
	v_exp_f32_e32 v40, v241
	v_exp_f32_e32 v32, v229
	v_exp_f32_e32 v61, v214
	v_exp_f32_e32 v46, v242
	v_exp_f32_e32 v44, v215
	v_add_f32_e32 v109, v133, v125
	v_exp_f32_e32 v42, v243
	v_mov_b32_e32 v33, v225
	v_pk_add_f32 v[62:63], v[108:109], v[32:33]
	v_add_f32_e32 v111, v134, v126
	v_pk_add_f32 v[62:63], v[62:63], v[62:63] op_sel_hi:[0,1]
	v_mov_b32_e32 v49, v63
	v_pk_add_f32 v[62:63], v[110:111], v[48:49]
	v_add_f32_e32 v113, v135, v127
	v_pk_add_f32 v[62:63], v[62:63], v[62:63] op_sel_hi:[0,1]
	v_mov_b32_e32 v51, v63
	v_pk_add_f32 v[62:63], v[112:113], v[50:51]
	v_add_f32_e32 v131, v136, v129
	v_pk_add_f32 v[62:63], v[62:63], v[62:63] op_sel_hi:[0,1]
	v_mov_b32_e32 v53, v63
	v_add3_u32 v47, s8, v116, v117
	v_exp_f32_e32 v34, v132
	v_pk_add_f32 v[62:63], v[130:131], v[52:53]
	v_cvt_pk_bf16_f32 v108, v133, v108
	v_cvt_pk_bf16_f32 v109, v134, v110
	v_cvt_pk_bf16_f32 v110, v135, v112
	v_cvt_pk_bf16_f32 v111, v136, v130
	ds_read_b64_tr_b16 v[130:131], v47 offset:13312
	ds_read_b64_tr_b16 v[132:133], v47 offset:14464
	ds_read_b64_tr_b16 v[134:135], v47 offset:13376
	ds_read_b64_tr_b16 v[136:137], v47 offset:14528
	v_pk_mul_f32 v[14:15], v[14:15], v[34:35] op_sel_hi:[1,0]
	v_pk_mul_f32 v[12:13], v[12:13], v[34:35] op_sel_hi:[1,0]
	v_pk_mul_f32 v[10:11], v[10:11], v[34:35] op_sel_hi:[1,0]
	v_pk_mul_f32 v[8:9], v[8:9], v[34:35] op_sel_hi:[1,0]
	v_pk_mul_f32 v[6:7], v[6:7], v[34:35] op_sel_hi:[1,0]
	v_pk_mul_f32 v[4:5], v[4:5], v[34:35] op_sel_hi:[1,0]
	v_pk_mul_f32 v[2:3], v[2:3], v[34:35] op_sel_hi:[1,0]
	v_pk_mul_f32 v[0:1], v[0:1], v[34:35] op_sel_hi:[1,0]
	v_pk_mul_f32 v[30:31], v[30:31], v[34:35] op_sel_hi:[1,0]
	v_pk_mul_f32 v[28:29], v[28:29], v[34:35] op_sel_hi:[1,0]
	v_pk_mul_f32 v[26:27], v[26:27], v[34:35] op_sel_hi:[1,0]
	v_pk_mul_f32 v[24:25], v[24:25], v[34:35] op_sel_hi:[1,0]
	v_pk_mul_f32 v[22:23], v[22:23], v[34:35] op_sel_hi:[1,0]
	v_pk_mul_f32 v[20:21], v[20:21], v[34:35] op_sel_hi:[1,0]
	v_pk_mul_f32 v[18:19], v[18:19], v[34:35] op_sel_hi:[1,0]
	v_pk_mul_f32 v[16:17], v[16:17], v[34:35] op_sel_hi:[1,0]
	s_waitcnt lgkmcnt(2)
; #define LAS __attribute__((address_space(3)))
; #define MFMA32(a, b, c) __builtin_amdgcn_mfma_f32_32x32x16_bf16((a), (b), (c), 0, 0, 0)
; DI bf16x8 tr_frag(LAS const unsigned char* p, int hi_off) { s16x4 lo = trr(p), hi = trr(p + hi_off); return __builtin_shufflevector(lo, hi, 0, 1, 2, 3, 4, 5, 6, 7); }
; DI void mla_item(int g_wave, LAS unsigned char* lds, const bf16_t* QN, const bf16_t* QR, const bf16_t* KN, const bf16_t* KRb, const bf16_t* VM, bf16_t* MIX,
;                  int kvbase, int qrow0, int nq, int head, int ntiles, int wt) {
;     ...
;             l_run = l_run * alpha + ls;
; #pragma unroll
;             for (int i = 0; i < 16; ++i) { o0[i] *= alpha; o1[i] *= alpha; }
;             LAS const unsigned char* vb = base + KB;
; #pragma unroll
;             for (int kt = 0; kt < 2; ++kt)
; #pragma unroll
;                 for (int ss = 0; ss < 2; ++ss) {
;                     const bf16x8 pb = packfrag(kt == 0 ? s0 : s1, ss);
;                     LAS const unsigned char* vp = vb + (32 * kt + 16 * ss + 4 * h + tq) * VST + (16 * blk + 4 * tp) * 2;
;                     const bf16x8 a0 = tr_frag(vp, 8 * VST), a1 = tr_frag(vp + 64, 8 * VST);
;                     o0 = MFMA32(a0, pb, o0); o1 = MFMA32(a1, pb, o1);
;                 }
	v_mfma_f32_32x32x16_bf16 v[0:15], v[130:133], v[108:111], v[0:15]
	v_pk_add_f32 v[62:63], v[62:63], v[62:63] op_sel_hi:[0,1]
	v_add_f32_e32 v55, v138, v35
	v_mov_b32_e32 v37, v63
	v_pk_add_f32 v[62:63], v[54:55], v[36:37]
	v_add_f32_e32 v57, v139, v128
	v_pk_add_f32 v[62:63], v[62:63], v[62:63] op_sel_hi:[0,1]
	v_mov_b32_e32 v39, v63
	s_waitcnt lgkmcnt(0)
	v_mfma_f32_32x32x16_bf16 v[16:31], v[134:137], v[108:111], v[16:31]
	ds_read_b64_tr_b16 v[108:109], v47 offset:15616
	ds_read_b64_tr_b16 v[110:111], v47 offset:16768
	ds_read_b64_tr_b16 v[130:131], v47 offset:15680
	ds_read_b64_tr_b16 v[132:133], v47 offset:16832
	v_add_f32_e64 v62, v56, v38
	v_add_f32_e64 v63, v57, v39
	v_cvt_pk_bf16_f32 v54, v138, v54
	v_cvt_pk_bf16_f32 v55, v139, v56
	v_cvt_pk_bf16_f32 v56, v140, v58
	v_cvt_pk_bf16_f32 v57, v61, v44
	v_pk_add_f32 v[62:63], v[62:63], v[62:63] op_sel_hi:[0,1]
	v_add_f32_e32 v59, v140, v60
	s_waitcnt lgkmcnt(2)
	v_mfma_f32_32x32x16_bf16 v[0:15], v[108:111], v[54:57], v[0:15]
	v_mov_b32_e32 v41, v63
	v_add_f32_e64 v62, v58, v40
	v_add_f32_e64 v63, v59, v41
	v_add_f32_e32 v45, v61, v46
	v_pk_add_f32 v[62:63], v[62:63], v[62:63] op_sel_hi:[0,1]
	v_mov_b32_e32 v43, v63
	v_pk_add_f32 v[62:63], v[44:45], v[42:43]
	v_cvt_pk_bf16_f32 v37, v128, v38
	s_waitcnt lgkmcnt(0)
	v_mfma_f32_32x32x16_bf16 v[16:31], v[130:133], v[54:57], v[16:31]
	v_cvt_pk_bf16_f32 v55, v126, v48
	v_cvt_pk_bf16_f32 v56, v127, v50
	ds_read_b64_tr_b16 v[48:49], v47 offset:17920
	ds_read_b64_tr_b16 v[50:51], v47 offset:19072
	ds_read_b64_tr_b16 v[108:109], v47 offset:17984
	ds_read_b64_tr_b16 v[110:111], v47 offset:19136
	v_cvt_pk_bf16_f32 v54, v125, v32
	v_cvt_pk_bf16_f32 v57, v129, v52
	v_cvt_pk_bf16_f32 v38, v60, v40
	v_cvt_pk_bf16_f32 v39, v46, v42
	s_waitcnt lgkmcnt(2)
	v_mfma_f32_32x32x16_bf16 v[0:15], v[48:51], v[54:57], v[0:15]
	ds_read_b64_tr_b16 v[40:41], v47 offset:20224
	ds_read_b64_tr_b16 v[42:43], v47 offset:21376
	ds_read_b64_tr_b16 v[44:45], v47 offset:20288
	ds_read_b64_tr_b16 v[46:47], v47 offset:21440
	v_cvt_pk_bf16_f32 v36, v35, v36
	v_add_f32_e32 v33, v62, v63
	v_fmac_f32_e32 v33, v115, v34
	v_mov_b32_e32 v115, v33
	s_waitcnt lgkmcnt(4)
	v_mfma_f32_32x32x16_bf16 v[16:31], v[108:111], v[54:57], v[16:31]
	v_mov_b32_e32 v108, v124
	s_waitcnt lgkmcnt(2)
	v_mfma_f32_32x32x16_bf16 v[0:15], v[40:43], v[36:39], v[0:15]
	s_waitcnt lgkmcnt(0)
	v_mfma_f32_32x32x16_bf16 v[16:31], v[44:47], v[36:39], v[16:31]
